# v03 + gla_job chunk loop: LDS reads software-pipelined 6 deep into dead prefetch registers, counted lgkmcnt waits
# speedup vs baseline: 1.0055x; 1.0046x over previous
.LBB0_707:
	ds_read_b64_tr_b16 v[134:135], v211
	ds_read_b64_tr_b16 v[136:137], v211 offset:1088
	ds_read_b64_tr_b16 v[130:131], v211 offset:8704
	ds_read_b64_tr_b16 v[132:133], v211 offset:9792
	v_mov_b32_e32 v138, 0
	s_andn2_b64 vcc, exec, s[18:19]
	v_mov_b32_e32 v140, 0
	v_mov_b32_e32 v141, 0
	v_mov_b32_e32 v142, 0
	v_mov_b32_e32 v143, 0
	s_cbranch_vccnz .LBB0_709
	ds_read_b128 v[102:105], v221
	ds_read_b128 v[106:109], v232
	ds_read_b128 v[110:113], v221 offset:64
	ds_read_b128 v[114:117], v232 offset:64
	ds_read_b128 v[118:121], v221 offset:128
	ds_read_b128 v[122:125], v232 offset:128
	s_nop 0
	s_nop 0
	s_waitcnt lgkmcnt(6)
	s_waitcnt lgkmcnt(4)
	v_mfma_f32_16x16x32_bf16 v[140:143], v[102:105], v[106:109], 0
	ds_read_b128 v[102:105], v221 offset:192
	ds_read_b128 v[106:109], v232 offset:192
	s_nop 0
	s_nop 0
	s_nop 0
	s_waitcnt lgkmcnt(4)
	v_mfma_f32_16x16x32_bf16 v[140:143], v[110:113], v[114:117], v[140:143]
	ds_read_b128 v[110:113], v221 offset:256
	ds_read_b128 v[114:117], v232 offset:256
	s_nop 0
	s_nop 0
	s_nop 0
	s_waitcnt lgkmcnt(4)
	v_mfma_f32_16x16x32_bf16 v[140:143], v[118:121], v[122:125], v[140:143]
	ds_read_b128 v[118:121], v221 offset:320
	ds_read_b128 v[122:125], v232 offset:320
	s_nop 0
	s_nop 0
	s_nop 0
	s_waitcnt lgkmcnt(4)
	v_mfma_f32_16x16x32_bf16 v[140:143], v[102:105], v[106:109], v[140:143]
	ds_read_b128 v[102:105], v221 offset:384
	ds_read_b128 v[106:109], v232 offset:384
	s_nop 0
	s_nop 0
	s_nop 0
	s_waitcnt lgkmcnt(4)
	v_mfma_f32_16x16x32_bf16 v[140:143], v[110:113], v[114:117], v[140:143]
	s_nop 0
	s_nop 0
	s_nop 0
	s_waitcnt lgkmcnt(2)
	v_mfma_f32_16x16x32_bf16 v[140:143], v[118:121], v[122:125], v[140:143]
	s_nop 0
	s_nop 0
	s_nop 0
	s_waitcnt lgkmcnt(0)
	v_mfma_f32_16x16x32_bf16 v[140:143], v[102:105], v[106:109], v[140:143]
	ds_read_b128 v[144:147], v221 offset:448
	ds_read_b128 v[148:151], v232 offset:448
	s_nop 0
	s_waitcnt lgkmcnt(0)
	v_mfma_f32_16x16x32_bf16 v[140:143], v[144:147], v[148:151], v[140:143]
.LBB0_709:
	s_nop 7
	v_cndmask_b32_e64 v1, v140, 0, s[40:41]
	v_cndmask_b32_e64 v35, 0, v141, s[42:43]
	v_cndmask_b32_e64 v1, v1, v140, s[42:43]
	v_cndmask_b32_e64 v37, v142, 0, s[44:45]
	v_cndmask_b32_e64 v139, v143, 0, s[46:47]
	v_cvt_pk_bf16_f32 v36, v1, v35
	v_cvt_pk_bf16_f32 v37, v37, v139
	s_andn2_b64 vcc, exec, s[20:21]
	v_mov_b32_e32 v139, 0
	v_mov_b32_e32 v140, 0
	v_mov_b32_e32 v141, 0
	ds_write_b64 v212, v[36:37]
	s_cbranch_vccnz .LBB0_711
	ds_read_b128 v[102:105], v221 offset:8448
	ds_read_b128 v[106:109], v232
	ds_read_b128 v[110:113], v221 offset:8512
	ds_read_b128 v[114:117], v232 offset:64
	ds_read_b128 v[118:121], v221 offset:8576
	ds_read_b128 v[122:125], v232 offset:128
	s_nop 0
	s_nop 0
	s_waitcnt lgkmcnt(6)
	s_waitcnt lgkmcnt(4)
	v_mfma_f32_16x16x32_bf16 v[138:141], v[102:105], v[106:109], 0
	ds_read_b128 v[102:105], v221 offset:8640
	ds_read_b128 v[106:109], v232 offset:192
	s_nop 0
	s_nop 0
	s_nop 0
	s_waitcnt lgkmcnt(4)
	v_mfma_f32_16x16x32_bf16 v[138:141], v[110:113], v[114:117], v[138:141]
	ds_read_b128 v[110:113], v221 offset:8704
	ds_read_b128 v[114:117], v232 offset:256
	s_nop 0
	s_nop 0
	s_nop 0
	s_waitcnt lgkmcnt(4)
	v_mfma_f32_16x16x32_bf16 v[138:141], v[118:121], v[122:125], v[138:141]
	ds_read_b128 v[118:121], v221 offset:8768
	ds_read_b128 v[122:125], v232 offset:320
	s_nop 0
	s_nop 0
	s_nop 0
	s_waitcnt lgkmcnt(4)
	v_mfma_f32_16x16x32_bf16 v[138:141], v[102:105], v[106:109], v[138:141]
	ds_read_b128 v[102:105], v221 offset:8832
	ds_read_b128 v[106:109], v232 offset:384
	s_nop 0
	s_nop 0
	s_nop 0
	s_waitcnt lgkmcnt(4)
	v_mfma_f32_16x16x32_bf16 v[138:141], v[110:113], v[114:117], v[138:141]
	s_nop 0
	s_nop 0
	s_nop 0
	s_waitcnt lgkmcnt(2)
	v_mfma_f32_16x16x32_bf16 v[138:141], v[118:121], v[122:125], v[138:141]
	s_nop 0
	s_nop 0
	s_nop 0
	s_waitcnt lgkmcnt(0)
	v_mfma_f32_16x16x32_bf16 v[138:141], v[102:105], v[106:109], v[138:141]
	ds_read_b128 v[142:145], v221 offset:8896
	ds_read_b128 v[146:149], v232 offset:448
	s_nop 0
	s_waitcnt lgkmcnt(0)
	v_mfma_f32_16x16x32_bf16 v[138:141], v[142:145], v[146:149], v[138:141]
.LBB0_711:
	s_nop 7
	v_cndmask_b32_e64 v1, v138, 0, s[48:49]
	v_cndmask_b32_e64 v35, v139, 0, s[50:51]
	v_cndmask_b32_e64 v37, v140, 0, s[52:53]
	v_cndmask_b32_e64 v138, v141, 0, s[54:55]
	v_cvt_pk_bf16_f32 v36, v1, v35
	v_cvt_pk_bf16_f32 v37, v37, v138
	ds_write_b64 v213, v[36:37]
	ds_read_b128 v[102:105], v155
	ds_read_b128 v[106:109], v180
	ds_read2_b64 v[110:113], v157 offset1:4
	s_nop 0
	s_nop 0
	v_add_u32_e32 v1, 0x2000, v157
	ds_read2_b64 v[114:117], v1 offset0:32 offset1:36
	v_add_u32_e32 v35, 0x4000, v157
	ds_read2_b64 v[118:121], v35 offset0:64 offset1:68
	v_add_u32_e32 v246, 0x6000, v157
	ds_read2_b64 v[122:125], v246 offset0:96 offset1:100
	s_waitcnt lgkmcnt(7)
	s_waitcnt lgkmcnt(5)
	v_pk_mul_f32 v[36:37], v[4:5], v[104:105]
	ds_read_b128 v[126:129], v181
	v_pk_mul_f32 v[138:139], v[2:3], v[102:103]
	s_waitcnt lgkmcnt(5)
	v_pk_mul_f32 v[140:141], v[10:11], v[106:107]
	ds_read_b128 v[102:105], v182
	v_cvt_pk_bf16_f32 v138, v138, v139
	v_cvt_pk_bf16_f32 v139, v36, v37
	v_pk_mul_f32 v[36:37], v[12:13], v[108:109]
	v_cvt_pk_bf16_f32 v140, v140, v141
	v_cvt_pk_bf16_f32 v141, v36, v37
	s_nop 0
	s_nop 0
	s_nop 0
	s_nop 0
	s_nop 0
	s_waitcnt lgkmcnt(5)
	v_mfma_f32_16x16x32_bf16 v[142:145], v[138:141], v[110:113], 0
	ds_read2_b64 v[106:109], v157 offset0:8 offset1:12
	s_andn2_b64 vcc, exec, s[22:23]
	s_waitcnt lgkmcnt(5)
	v_mfma_f32_16x16x32_bf16 v[146:149], v[138:141], v[114:117], 0
	ds_read2_b64 v[110:113], v1 offset0:40 offset1:44
	s_waitcnt lgkmcnt(5)
	v_mfma_f32_16x16x32_bf16 v[150:153], v[138:141], v[118:121], 0
	ds_read2_b64 v[114:117], v35 offset0:72 offset1:76
	s_waitcnt lgkmcnt(5)
	v_mfma_f32_16x16x32_bf16 v[138:141], v[138:141], v[122:125], 0
	ds_read2_b64 v[118:121], v246 offset0:104 offset1:108
	s_nop 0
	s_nop 0
	s_nop 0
	s_waitcnt lgkmcnt(5)
	v_pk_mul_f32 v[36:37], v[8:9], v[128:129]
	ds_read_b128 v[122:125], v183
	v_pk_mul_f32 v[234:235], v[6:7], v[126:127]
	s_waitcnt lgkmcnt(5)
	v_pk_mul_f32 v[236:237], v[14:15], v[102:103]
	ds_read_b128 v[126:129], v184
	v_cvt_pk_bf16_f32 v234, v234, v235
	v_cvt_pk_bf16_f32 v235, v36, v37
	v_pk_mul_f32 v[36:37], v[16:17], v[104:105]
	v_cvt_pk_bf16_f32 v236, v236, v237
	v_cvt_pk_bf16_f32 v237, v36, v37
	s_nop 0
	s_nop 0
	s_waitcnt lgkmcnt(5)
	v_mfma_f32_16x16x32_bf16 v[142:145], v[234:237], v[106:109], v[142:145]
	ds_read2_b64 v[102:105], v157 offset0:16 offset1:20
	s_nop 0
	s_nop 0
	s_waitcnt lgkmcnt(5)
	v_mfma_f32_16x16x32_bf16 v[146:149], v[234:237], v[110:113], v[146:149]
	ds_read2_b64 v[106:109], v1 offset0:48 offset1:52
	s_nop 0
	s_nop 0
	s_waitcnt lgkmcnt(5)
	v_mfma_f32_16x16x32_bf16 v[150:153], v[234:237], v[114:117], v[150:153]
	ds_read2_b64 v[110:113], v35 offset0:80 offset1:84
	s_nop 0
	s_nop 0
	s_waitcnt lgkmcnt(5)
	v_mfma_f32_16x16x32_bf16 v[138:141], v[234:237], v[118:121], v[138:141]
	ds_read2_b64 v[114:117], v246 offset0:112 offset1:116
	s_nop 0
	s_nop 0
	s_nop 0
	s_waitcnt lgkmcnt(5)
	v_pk_mul_f32 v[36:37], v[20:21], v[124:125]
	ds_read_b128 v[118:121], v185
	v_pk_mul_f32 v[234:235], v[18:19], v[122:123]
	s_waitcnt lgkmcnt(5)
	v_pk_mul_f32 v[236:237], v[22:23], v[126:127]
	ds_read_b128 v[122:125], v186
	v_cvt_pk_bf16_f32 v234, v234, v235
	v_cvt_pk_bf16_f32 v235, v36, v37
	v_pk_mul_f32 v[36:37], v[24:25], v[128:129]
	v_cvt_pk_bf16_f32 v236, v236, v237
	v_cvt_pk_bf16_f32 v237, v36, v37
	s_nop 0
	s_nop 0
	s_waitcnt lgkmcnt(5)
	v_mfma_f32_16x16x32_bf16 v[142:145], v[234:237], v[102:105], v[142:145]
	ds_read2_b64 v[102:105], v157 offset0:24 offset1:28
	s_nop 0
	s_nop 0
	s_waitcnt lgkmcnt(5)
	v_mfma_f32_16x16x32_bf16 v[146:149], v[234:237], v[106:109], v[146:149]
	ds_read2_b64 v[106:109], v1 offset0:56 offset1:60
	s_nop 0
	s_nop 0
	s_waitcnt lgkmcnt(5)
	v_mfma_f32_16x16x32_bf16 v[150:153], v[234:237], v[110:113], v[150:153]
	ds_read2_b64 v[110:113], v35 offset0:88 offset1:92
	s_nop 0
	s_nop 0
	s_waitcnt lgkmcnt(5)
	v_mfma_f32_16x16x32_bf16 v[138:141], v[234:237], v[114:117], v[138:141]
	ds_read2_b64 v[114:117], v246 offset0:120 offset1:124
	s_nop 0
	s_nop 0
	s_nop 0
	s_waitcnt lgkmcnt(5)
	v_pk_mul_f32 v[36:37], v[28:29], v[120:121]
	ds_read_b128 v[126:129], v187
	v_pk_mul_f32 v[234:235], v[26:27], v[118:119]
	s_waitcnt lgkmcnt(5)
	v_pk_mul_f32 v[236:237], v[30:31], v[122:123]
	ds_read_b128 v[118:121], v188
	v_cvt_pk_bf16_f32 v234, v234, v235
	v_cvt_pk_bf16_f32 v235, v36, v37
	v_pk_mul_f32 v[36:37], v[32:33], v[124:125]
	v_cvt_pk_bf16_f32 v236, v236, v237
	v_cvt_pk_bf16_f32 v237, v36, v37
	s_nop 0
	s_nop 0
	s_waitcnt lgkmcnt(5)
	v_mfma_f32_16x16x32_bf16 v[142:145], v[234:237], v[102:105], v[142:145]
	ds_read2_b64 v[102:105], v157 offset0:32 offset1:36
	s_nop 0
	s_nop 0
	s_waitcnt lgkmcnt(5)
	v_mfma_f32_16x16x32_bf16 v[146:149], v[234:237], v[106:109], v[146:149]
	ds_read2_b64 v[106:109], v1 offset0:64 offset1:68
	s_nop 0
	s_nop 0
	s_waitcnt lgkmcnt(5)
	v_mfma_f32_16x16x32_bf16 v[150:153], v[234:237], v[110:113], v[150:153]
	ds_read2_b64 v[110:113], v35 offset0:96 offset1:100
	s_nop 0
	s_nop 0
	s_waitcnt lgkmcnt(5)
	v_mfma_f32_16x16x32_bf16 v[138:141], v[234:237], v[114:117], v[138:141]
	ds_read2_b64 v[114:117], v246 offset0:128 offset1:132
	s_nop 0
	s_nop 0
	s_nop 0
	s_waitcnt lgkmcnt(5)
	v_pk_mul_f32 v[36:37], v[40:41], v[128:129]
	ds_read_b128 v[122:125], v189
	v_pk_mul_f32 v[234:235], v[38:39], v[126:127]
	s_waitcnt lgkmcnt(5)
	v_pk_mul_f32 v[236:237], v[42:43], v[118:119]
	ds_read_b128 v[126:129], v190
	v_cvt_pk_bf16_f32 v234, v234, v235
	v_cvt_pk_bf16_f32 v235, v36, v37
	v_pk_mul_f32 v[36:37], v[44:45], v[120:121]
	v_cvt_pk_bf16_f32 v236, v236, v237
	v_cvt_pk_bf16_f32 v237, v36, v37
	s_nop 0
	s_nop 0
	s_waitcnt lgkmcnt(5)
	v_mfma_f32_16x16x32_bf16 v[142:145], v[234:237], v[102:105], v[142:145]
	ds_read2_b64 v[102:105], v157 offset0:40 offset1:44
	s_nop 0
	s_nop 0
	s_waitcnt lgkmcnt(5)
	v_mfma_f32_16x16x32_bf16 v[146:149], v[234:237], v[106:109], v[146:149]
	ds_read2_b64 v[106:109], v1 offset0:72 offset1:76
	s_nop 0
	s_nop 0
	s_waitcnt lgkmcnt(5)
	v_mfma_f32_16x16x32_bf16 v[150:153], v[234:237], v[110:113], v[150:153]
	ds_read2_b64 v[110:113], v35 offset0:104 offset1:108
	s_nop 0
	s_nop 0
	s_waitcnt lgkmcnt(5)
	v_mfma_f32_16x16x32_bf16 v[138:141], v[234:237], v[114:117], v[138:141]
	ds_read2_b64 v[114:117], v246 offset0:136 offset1:140
	s_nop 0
	s_nop 0
	s_nop 0
	s_waitcnt lgkmcnt(5)
	v_pk_mul_f32 v[36:37], v[48:49], v[124:125]
	ds_read_b128 v[118:121], v191
	v_pk_mul_f32 v[234:235], v[46:47], v[122:123]
	s_waitcnt lgkmcnt(5)
	v_pk_mul_f32 v[236:237], v[50:51], v[126:127]
	ds_read_b128 v[122:125], v192
	v_cvt_pk_bf16_f32 v234, v234, v235
	v_cvt_pk_bf16_f32 v235, v36, v37
	v_pk_mul_f32 v[36:37], v[52:53], v[128:129]
	v_cvt_pk_bf16_f32 v236, v236, v237
	v_cvt_pk_bf16_f32 v237, v36, v37
	s_nop 0
	s_nop 0
	s_waitcnt lgkmcnt(5)
	v_mfma_f32_16x16x32_bf16 v[142:145], v[234:237], v[102:105], v[142:145]
	ds_read2_b64 v[102:105], v157 offset0:48 offset1:52
	s_nop 0
	s_nop 0
	s_waitcnt lgkmcnt(5)
	v_mfma_f32_16x16x32_bf16 v[146:149], v[234:237], v[106:109], v[146:149]
	ds_read2_b64 v[106:109], v1 offset0:80 offset1:84
	s_nop 0
	s_nop 0
	s_waitcnt lgkmcnt(5)
	v_mfma_f32_16x16x32_bf16 v[150:153], v[234:237], v[110:113], v[150:153]
	ds_read2_b64 v[110:113], v35 offset0:112 offset1:116
	s_nop 0
	s_nop 0
	s_waitcnt lgkmcnt(5)
	v_mfma_f32_16x16x32_bf16 v[138:141], v[234:237], v[114:117], v[138:141]
	ds_read2_b64 v[114:117], v246 offset0:144 offset1:148
	s_nop 0
	s_nop 0
	s_nop 0
	s_waitcnt lgkmcnt(5)
	v_pk_mul_f32 v[36:37], v[56:57], v[120:121]
	ds_read_b128 v[126:129], v193
	v_pk_mul_f32 v[234:235], v[54:55], v[118:119]
	s_waitcnt lgkmcnt(5)
	v_pk_mul_f32 v[236:237], v[58:59], v[122:123]
	ds_read_b128 v[118:121], v194
	v_cvt_pk_bf16_f32 v234, v234, v235
	v_cvt_pk_bf16_f32 v235, v36, v37
	v_pk_mul_f32 v[36:37], v[60:61], v[124:125]
	v_cvt_pk_bf16_f32 v236, v236, v237
	v_cvt_pk_bf16_f32 v237, v36, v37
	s_nop 0
	s_nop 0
	s_waitcnt lgkmcnt(5)
	v_mfma_f32_16x16x32_bf16 v[142:145], v[234:237], v[102:105], v[142:145]
	ds_read2_b64 v[102:105], v157 offset0:56 offset1:60
	s_nop 0
	s_nop 0
	s_waitcnt lgkmcnt(5)
	v_mfma_f32_16x16x32_bf16 v[146:149], v[234:237], v[106:109], v[146:149]
	s_nop 0
	s_nop 0
	s_waitcnt lgkmcnt(4)
	v_mfma_f32_16x16x32_bf16 v[238:241], v[234:237], v[110:113], v[150:153]
	s_nop 2
	s_nop 0
	s_nop 0
	s_waitcnt lgkmcnt(3)
	v_mfma_f32_16x16x32_bf16 v[138:141], v[234:237], v[114:117], v[138:141]
	s_nop 0
	s_nop 0
	s_nop 0
	s_waitcnt lgkmcnt(2)
	v_pk_mul_f32 v[36:37], v[64:65], v[128:129]
	v_pk_mul_f32 v[150:151], v[62:63], v[126:127]
	v_cvt_pk_bf16_f32 v243, v36, v37
	v_cvt_pk_bf16_f32 v242, v150, v151
	s_waitcnt lgkmcnt(1)
	v_pk_mul_f32 v[36:37], v[68:69], v[120:121]
	v_pk_mul_f32 v[150:151], v[66:67], v[118:119]
	v_cvt_pk_bf16_f32 v245, v36, v37
	v_cvt_pk_bf16_f32 v244, v150, v151
	s_nop 0
	ds_read2_b64 v[106:109], v1 offset0:88 offset1:92
	ds_read2_b64 v[234:237], v246 offset0:152 offset1:156
	s_nop 0
	s_waitcnt lgkmcnt(2)
	v_mfma_f32_16x16x32_bf16 v[150:153], v[242:245], v[102:105], v[142:145]
	s_nop 2
	s_nop 0
	s_nop 0
	s_waitcnt lgkmcnt(1)
	v_mfma_f32_16x16x32_bf16 v[146:149], v[242:245], v[106:109], v[146:149]
	ds_read2_b64 v[142:145], v35 offset0:120 offset1:124
	s_waitcnt lgkmcnt(0)
	s_barrier
	v_mfma_f32_16x16x32_bf16 v[142:145], v[242:245], v[142:145], v[238:241]
	v_mfma_f32_16x16x32_bf16 v[138:141], v[242:245], v[234:237], v[138:141]
	s_cbranch_vccnz .LBB0_719
	v_mov_b32_e32 v1, v158
	s_mov_b32 s22, s79
	v_ashrrev_i32_e32 v35, 5, v1
	v_lshlrev_b32_e32 v1, 4, v1
	v_and_b32_e32 v1, 0x1f0, v1
	v_mul_lo_u32 v35, v35, s84
	v_add3_u32 v1, 0, v1, v35
	s_waitcnt vmcnt(0)
	ds_write_b128 v1, v[70:73]
	ds_write_b128 v1, v[74:77] offset:33792
	ds_write_b128 v1, v[78:81] offset:8448
	ds_write_b128 v1, v[82:85] offset:42240
	ds_write_b128 v1, v[86:89] offset:16896
	ds_write_b128 v1, v[90:93] offset:50688
	ds_write_b128 v1, v[94:97] offset:25344
	ds_write_b128 v1, v[98:101] offset:59136
	v_mov_b32_e32 v1, v158
	s_lshl_b32 s26, s22, 6
	s_add_i32 s22, s22, s75
	s_ashr_i32 s23, s22, 31
	s_ashr_i32 s27, s26, 31
	s_sub_i32 s80, s7, s26
	s_lshl_b64 s[24:25], s[22:23], 17
	s_add_u32 s24, s73, s24
	v_lshlrev_b32_e32 v36, 3, v1
	s_addc_u32 s25, s74, s25
	v_mov_b32_e32 v37, v34
	v_lshl_add_u64 v[110:111], v[36:37], 1, s[24:25]
	s_movk_i32 s24, 0x2000
	v_add_co_u32_e32 v106, vcc, s24, v110
	s_movk_i32 s24, 0x4000
	s_nop 0
	v_addc_co_u32_e32 v107, vcc, 0, v111, vcc
	v_add_co_u32_e32 v112, vcc, s24, v110
	s_movk_i32 s24, 0x6000
	s_nop 0
	v_addc_co_u32_e32 v113, vcc, 0, v111, vcc
	v_add_co_u32_e32 v114, vcc, s24, v110
	global_load_dwordx4 v[102:105], v[110:111], off
	s_nop 0
	global_load_dwordx4 v[106:109], v[106:107], off
	v_addc_co_u32_e32 v115, vcc, 0, v111, vcc
	global_load_dwordx4 v[110:113], v[112:113], off
	s_nop 0
	global_load_dwordx4 v[114:117], v[114:115], off
	v_ashrrev_i32_e32 v35, 4, v1
	v_and_b32_e32 v1, 0x78, v36
	s_add_u32 s24, s26, s71
	v_mov_b32_e32 v126, 0
	v_mov_b32_e32 v127, v34
	v_lshl_or_b32 v36, v35, 11, v1
	s_addc_u32 s25, s27, s72
	s_min_i32 s80, s80, 64
	v_mov_b32_e32 v128, v34
	v_mov_b32_e32 v129, v34
	v_mov_b64_e32 v[118:119], v[126:127]
	v_lshl_add_u64 v[36:37], v[36:37], 1, s[14:15]
	v_cmp_gt_i32_e32 vcc, s80, v35
	v_mov_b64_e32 v[120:121], v[128:129]
	s_and_saveexec_b64 s[26:27], vcc
	s_cbranch_execz .LBB0_714
	s_lshl_b64 s[82:83], s[24:25], 12
	v_lshl_add_u64 v[118:119], v[36:37], 0, s[82:83]
	global_load_dwordx4 v[118:121], v[118:119], off

.LBB0_735:
	s_or_b64 exec, exec, s[24:25]
	ds_read_b128 v[70:73], v163
	ds_read_b128 v[74:77], v218
	ds_read_b128 v[78:81], v218 offset:64
	ds_read_b128 v[82:85], v195
	ds_read_b128 v[86:89], v218 offset:2304
	ds_read_b128 v[90:93], v218 offset:2368
	s_nop 0
	v_cmp_gt_i32_e32 vcc, s26, v158
	s_and_b64 s[26:27], s[56:57], vcc
	s_waitcnt lgkmcnt(6)
	s_waitcnt lgkmcnt(5)
	v_pk_mul_f32 v[4:5], v[4:5], v[72:73]
	ds_read_b128 v[94:97], v196
	v_pk_mul_f32 v[2:3], v[2:3], v[70:71]
	s_nop 0
	s_nop 0
	s_waitcnt lgkmcnt(5)
	v_mfma_f32_16x16x32_bf16 v[2:5], v[74:77], v[134:137], v[2:5]
	ds_read_b128 v[70:73], v218 offset:4608
	s_nop 0
	s_nop 0
	s_waitcnt lgkmcnt(5)
	v_mfma_f32_16x16x32_bf16 v[2:5], v[78:81], v[130:133], v[2:5]
	ds_read_b128 v[74:77], v218 offset:4672
	s_nop 0
	s_nop 0
	s_waitcnt lgkmcnt(5)
	v_pk_mul_f32 v[12:13], v[12:13], v[84:85]
	ds_read_b128 v[78:81], v197
	v_pk_mul_f32 v[10:11], v[10:11], v[82:83]
	s_nop 0
	s_nop 0
	s_waitcnt lgkmcnt(5)
	v_mfma_f32_16x16x32_bf16 v[10:13], v[86:89], v[134:137], v[10:13]
	ds_read_b128 v[82:85], v218 offset:6912
	s_nop 0
	s_nop 0
	s_waitcnt lgkmcnt(5)
	v_mfma_f32_16x16x32_bf16 v[10:13], v[90:93], v[130:133], v[10:13]
	ds_read_b128 v[86:89], v218 offset:6976
	s_nop 0
	s_nop 0
	s_waitcnt lgkmcnt(5)
	v_pk_mul_f32 v[8:9], v[8:9], v[96:97]
	ds_read_b128 v[90:93], v198
	v_pk_mul_f32 v[6:7], v[6:7], v[94:95]
	s_nop 0
	s_nop 0
	s_waitcnt lgkmcnt(5)
	v_mfma_f32_16x16x32_bf16 v[6:9], v[70:73], v[134:137], v[6:9]
	ds_read_b128 v[70:73], v218 offset:9216
	s_nop 0
	s_nop 0
	s_waitcnt lgkmcnt(5)
	v_mfma_f32_16x16x32_bf16 v[6:9], v[74:77], v[130:133], v[6:9]
	ds_read_b128 v[74:77], v218 offset:9280
	s_nop 0
	s_nop 0
	s_waitcnt lgkmcnt(5)
	v_pk_mul_f32 v[16:17], v[16:17], v[80:81]
	ds_read_b128 v[94:97], v199
	v_pk_mul_f32 v[14:15], v[14:15], v[78:79]
	s_nop 0
	s_nop 0
	s_waitcnt lgkmcnt(5)
	v_mfma_f32_16x16x32_bf16 v[14:17], v[82:85], v[134:137], v[14:17]
	ds_read_b128 v[78:81], v218 offset:11520
	s_nop 0
	s_nop 0
	s_waitcnt lgkmcnt(5)
	v_mfma_f32_16x16x32_bf16 v[14:17], v[86:89], v[130:133], v[14:17]
	ds_read_b128 v[82:85], v218 offset:11584
	s_nop 0
	s_nop 0
	s_waitcnt lgkmcnt(5)
	v_pk_mul_f32 v[20:21], v[20:21], v[92:93]
	ds_read_b128 v[86:89], v200
	v_pk_mul_f32 v[18:19], v[18:19], v[90:91]
	s_nop 0
	s_nop 0
	s_waitcnt lgkmcnt(5)
	v_mfma_f32_16x16x32_bf16 v[18:21], v[70:73], v[134:137], v[18:21]
	ds_read_b128 v[70:73], v218 offset:13824
	s_nop 0
	s_nop 0
	s_waitcnt lgkmcnt(5)
	v_mfma_f32_16x16x32_bf16 v[18:21], v[74:77], v[130:133], v[18:21]
	ds_read_b128 v[74:77], v218 offset:13888
	s_nop 0
	s_nop 0
	s_waitcnt lgkmcnt(5)
	v_pk_mul_f32 v[24:25], v[24:25], v[96:97]
	ds_read_b128 v[90:93], v201
	v_pk_mul_f32 v[22:23], v[22:23], v[94:95]
	s_nop 0
	s_nop 0
	s_waitcnt lgkmcnt(5)
	v_mfma_f32_16x16x32_bf16 v[22:25], v[78:81], v[134:137], v[22:25]
	ds_read_b128 v[78:81], v218 offset:16128
	s_nop 0
	s_nop 0
	s_waitcnt lgkmcnt(5)
	v_mfma_f32_16x16x32_bf16 v[22:25], v[82:85], v[130:133], v[22:25]
	ds_read_b128 v[82:85], v218 offset:16192
	s_nop 0
	s_nop 0
	s_waitcnt lgkmcnt(5)
	v_pk_mul_f32 v[28:29], v[28:29], v[88:89]
	ds_read_b128 v[94:97], v202
	v_pk_mul_f32 v[26:27], v[26:27], v[86:87]
	s_nop 0
	s_nop 0
	s_waitcnt lgkmcnt(5)
	v_mfma_f32_16x16x32_bf16 v[26:29], v[70:73], v[134:137], v[26:29]
	ds_read_b128 v[70:73], v218 offset:18432
	s_nop 0
	s_nop 0
	s_waitcnt lgkmcnt(5)
	v_mfma_f32_16x16x32_bf16 v[26:29], v[74:77], v[130:133], v[26:29]
	ds_read_b128 v[74:77], v218 offset:18496
	s_nop 0
	s_nop 0
	s_waitcnt lgkmcnt(5)
	v_pk_mul_f32 v[32:33], v[32:33], v[92:93]
	ds_read_b128 v[86:89], v203
	v_pk_mul_f32 v[30:31], v[30:31], v[90:91]
	s_nop 0
	s_nop 0
	s_waitcnt lgkmcnt(5)
	v_mfma_f32_16x16x32_bf16 v[30:33], v[78:81], v[134:137], v[30:33]
	ds_read_b128 v[78:81], v218 offset:20736
	s_nop 0
	s_nop 0
	s_waitcnt lgkmcnt(5)
	v_mfma_f32_16x16x32_bf16 v[30:33], v[82:85], v[130:133], v[30:33]
	ds_read_b128 v[82:85], v218 offset:20800
	s_nop 0
	s_nop 0
	s_waitcnt lgkmcnt(5)
	v_pk_mul_f32 v[40:41], v[40:41], v[96:97]
	ds_read_b128 v[90:93], v204
	v_pk_mul_f32 v[38:39], v[38:39], v[94:95]
	s_nop 0
	s_nop 0
	s_waitcnt lgkmcnt(5)
	v_mfma_f32_16x16x32_bf16 v[36:39], v[70:73], v[134:137], v[38:41]
	ds_read_b128 v[70:73], v218 offset:23040
	s_nop 0
	s_nop 0
	s_waitcnt lgkmcnt(5)
	v_mfma_f32_16x16x32_bf16 v[38:41], v[74:77], v[130:133], v[36:39]
	ds_read_b128 v[74:77], v218 offset:23104
	s_nop 0
	s_nop 0
	s_waitcnt lgkmcnt(5)
	v_pk_mul_f32 v[44:45], v[44:45], v[88:89]
	ds_read_b128 v[94:97], v205
	v_pk_mul_f32 v[42:43], v[42:43], v[86:87]
	s_nop 0
	s_nop 0
	s_waitcnt lgkmcnt(5)
	v_mfma_f32_16x16x32_bf16 v[42:45], v[78:81], v[134:137], v[42:45]
	ds_read_b128 v[78:81], v218 offset:25344
	s_nop 0
	s_nop 0
	s_waitcnt lgkmcnt(5)
	v_mfma_f32_16x16x32_bf16 v[42:45], v[82:85], v[130:133], v[42:45]
	ds_read_b128 v[82:85], v218 offset:25408
	s_nop 0
	s_nop 0
	s_waitcnt lgkmcnt(5)
	v_pk_mul_f32 v[48:49], v[48:49], v[92:93]
	ds_read_b128 v[86:89], v206
	v_pk_mul_f32 v[46:47], v[46:47], v[90:91]
	s_nop 0
	s_nop 0
	s_waitcnt lgkmcnt(5)
	v_mfma_f32_16x16x32_bf16 v[46:49], v[70:73], v[134:137], v[46:49]
	ds_read_b128 v[70:73], v218 offset:27648
	s_nop 0
	s_nop 0
	s_waitcnt lgkmcnt(5)
	v_mfma_f32_16x16x32_bf16 v[46:49], v[74:77], v[130:133], v[46:49]
	ds_read_b128 v[74:77], v218 offset:27712
	s_nop 0
	s_nop 0
	s_waitcnt lgkmcnt(5)
	v_pk_mul_f32 v[52:53], v[52:53], v[96:97]
	ds_read_b128 v[90:93], v207
	v_pk_mul_f32 v[50:51], v[50:51], v[94:95]
	s_nop 0
	s_nop 0
	s_waitcnt lgkmcnt(5)
	v_mfma_f32_16x16x32_bf16 v[50:53], v[78:81], v[134:137], v[50:53]
	ds_read_b128 v[78:81], v218 offset:29952
	s_nop 0
	s_nop 0
	s_waitcnt lgkmcnt(5)
	v_mfma_f32_16x16x32_bf16 v[50:53], v[82:85], v[130:133], v[50:53]
	ds_read_b128 v[82:85], v218 offset:30016
	s_nop 0
	s_nop 0
	s_waitcnt lgkmcnt(5)
	v_pk_mul_f32 v[56:57], v[56:57], v[88:89]
	ds_read_b128 v[94:97], v208
	v_pk_mul_f32 v[54:55], v[54:55], v[86:87]
	s_nop 0
	s_nop 0
	s_waitcnt lgkmcnt(5)
	v_mfma_f32_16x16x32_bf16 v[54:57], v[70:73], v[134:137], v[54:57]
	ds_read_b128 v[70:73], v218 offset:32256
	s_nop 0
	s_nop 0
	s_waitcnt lgkmcnt(5)
	v_mfma_f32_16x16x32_bf16 v[54:57], v[74:77], v[130:133], v[54:57]
	ds_read_b128 v[74:77], v218 offset:32320
	s_nop 0
	s_nop 0
	s_waitcnt lgkmcnt(5)
	v_pk_mul_f32 v[60:61], v[60:61], v[92:93]
	ds_read_b128 v[86:89], v209
	v_pk_mul_f32 v[58:59], v[58:59], v[90:91]
	s_nop 0
	s_nop 0
	s_waitcnt lgkmcnt(5)
	v_mfma_f32_16x16x32_bf16 v[58:61], v[78:81], v[134:137], v[58:61]
	s_nop 0
	s_nop 0
	s_waitcnt lgkmcnt(4)
	v_mfma_f32_16x16x32_bf16 v[58:61], v[82:85], v[130:133], v[58:61]
	s_nop 0
	s_nop 0
	s_waitcnt lgkmcnt(3)
	v_pk_mul_f32 v[64:65], v[64:65], v[96:97]
	v_pk_mul_f32 v[62:63], v[62:63], v[94:95]
	s_nop 0
	s_nop 0
	s_waitcnt lgkmcnt(2)
	v_mfma_f32_16x16x32_bf16 v[62:65], v[70:73], v[134:137], v[62:65]
	s_nop 0
	s_nop 0
	s_waitcnt lgkmcnt(1)
	v_mfma_f32_16x16x32_bf16 v[62:65], v[74:77], v[130:133], v[62:65]
	s_nop 0
	s_nop 0
	s_waitcnt lgkmcnt(0)
	v_pk_mul_f32 v[68:69], v[68:69], v[88:89]
	v_pk_mul_f32 v[66:67], v[66:67], v[86:87]
	ds_read_b128 v[138:141], v218 offset:34560
	s_nop 0
	s_waitcnt lgkmcnt(0)
	v_mfma_f32_16x16x32_bf16 v[66:69], v[138:141], v[134:137], v[66:69]
	ds_read_b128 v[134:137], v218 offset:34624
	s_waitcnt lgkmcnt(0)
	s_barrier
	v_mfma_f32_16x16x32_bf16 v[66:69], v[134:137], v[130:133], v[66:69]
	s_and_saveexec_b64 s[24:25], s[26:27]
	s_cbranch_execz .LBB0_694
	ds_read_b128 v[130:133], v220
	ds_read_b128 v[134:137], v220 offset:16
	s_waitcnt lgkmcnt(0)
	v_mov_b32_e32 v36, v130
	v_mov_b32_e32 v37, v134
	v_mov_b32_e32 v134, v131
	v_mov_b32_e32 v130, v132
	v_mov_b32_e32 v131, v136
	v_mov_b32_e32 v136, v133
	v_pk_add_f32 v[36:37], v[36:37], v[134:135]
	v_pk_add_f32 v[130:131], v[130:131], v[136:137]
	s_nop 0
	v_pk_add_f32 v[36:37], v[36:37], v[130:131]
	s_nop 0
	v_add_f32_e32 v1, v36, v37
	v_lshl_add_u64 v[36:37], s[22:23], 0, v[158:159]
	v_lshlrev_b64 v[36:37], 7, v[36:37]
	v_lshl_add_u64 v[36:37], s[16:17], 0, v[36:37]
	global_store_dword v[36:37], v1, off
	s_branch .LBB0_694
